# back-edge rotation of both attention tile loops on top of priority flips + counted lgkmcnt waits
# speedup vs baseline: 1.0093x; 1.0093x over previous
.LBB0_598:
	v_add_f32_e32 v184, v18, v19
	v_lshlrev_b32_e32 v18, 1, v50
	v_and_b32_e32 v18, 32, v18
	v_and_or_b32 v18, v51, s66, v18
	v_and_b32_e32 v19, 0x100, v52
	v_fmac_f32_e32 v184, 0, v56
	v_or3_b32 v187, v18, v19, v53
	s_add_i32 s35, 0, 0xc000
	v_cmp_gt_u32_e64 s[4:5], 32, v50
	v_lshl_add_u32 v186, v54, 2, s18
	v_lshlrev_b32_e32 v185, 4, v55
	v_mov_b64_e32 v[32:33], v[16:17]
	v_mov_b64_e32 v[48:49], v[16:17]
	v_mov_b64_e32 v[64:65], v[16:17]
	s_mov_b32 s96, 1
	v_add_u32_e32 v193, s35, v187
	s_lshl_b32 s97, s12, 8
	s_mov_b32 s12, 0x8000
	s_movk_i32 s74, 0x4000
	s_mov_b32 s0, 0
	v_mov_b64_e32 v[30:31], v[14:15]
	v_mov_b64_e32 v[28:29], v[12:13]
	v_mov_b64_e32 v[26:27], v[10:11]
	v_mov_b64_e32 v[24:25], v[8:9]
	v_mov_b64_e32 v[22:23], v[6:7]
	v_mov_b64_e32 v[20:21], v[4:5]
	v_mov_b64_e32 v[18:19], v[2:3]
	v_mov_b64_e32 v[46:47], v[14:15]
	v_mov_b64_e32 v[44:45], v[12:13]
	v_mov_b64_e32 v[42:43], v[10:11]
	v_mov_b64_e32 v[40:41], v[8:9]
	v_mov_b64_e32 v[38:39], v[6:7]
	v_mov_b64_e32 v[36:37], v[4:5]
	v_mov_b64_e32 v[34:35], v[2:3]
	v_mov_b64_e32 v[62:63], v[14:15]
	v_mov_b64_e32 v[60:61], v[12:13]
	v_mov_b64_e32 v[58:59], v[10:11]
	v_mov_b64_e32 v[56:57], v[8:9]
	v_mov_b64_e32 v[54:55], v[6:7]
	v_mov_b64_e32 v[52:53], v[4:5]
	v_mov_b64_e32 v[50:51], v[2:3]
	s_mov_b32 s75, s74
	s_mov_b32 s74, s0
	v_add_u32_e32 v238, s74, v193
.LBB0_599:
	s_barrier
	s_setprio 3
	ds_read_b128 v[82:85], v188 offset:40960
	ds_read_b128 v[210:213], v188 offset:45056
	ds_read_b128 v[214:217], v189 offset:40960
	ds_read_b128 v[218:221], v189 offset:45056
	ds_read_b128 v[222:225], v190 offset:40960
	ds_read_b128 v[226:229], v190 offset:45056
	ds_read_b128 v[230:233], v191 offset:40960
	ds_read_b128 v[234:237], v191 offset:45056
	ds_read_b64_tr_b16 v[194:195], v238 offset:0
	ds_read_b64_tr_b16 v[196:197], v238 offset:0x800
	ds_read_b64_tr_b16 v[198:199], v238 offset:0x1000
	ds_read_b64_tr_b16 v[200:201], v238 offset:0x1800
	s_waitcnt lgkmcnt(11)
	v_mfma_f32_32x32x16_bf16 v[98:113], v[82:85], v[126:129], v[66:81]
	s_waitcnt lgkmcnt(10)
	v_mfma_f32_32x32x16_bf16 v[82:97], v[210:213], v[126:129], v[66:81]
	ds_read_b64_tr_b16 v[202:203], v238 offset:0x2000
	ds_read_b64_tr_b16 v[204:205], v238 offset:0x2800
	ds_read_b64_tr_b16 v[206:207], v238 offset:0x3000
	ds_read_b64_tr_b16 v[208:209], v238 offset:0x3800
	s_waitcnt lgkmcnt(13)
	v_mfma_f32_32x32x16_bf16 v[98:113], v[214:217], v[122:125], v[98:113]
	s_waitcnt lgkmcnt(12)
	v_mfma_f32_32x32x16_bf16 v[82:97], v[218:221], v[122:125], v[82:97]
	s_waitcnt lgkmcnt(11)
	v_mfma_f32_32x32x16_bf16 v[98:113], v[222:225], v[118:121], v[98:113]
	s_waitcnt lgkmcnt(10)
	v_mfma_f32_32x32x16_bf16 v[82:97], v[226:229], v[118:121], v[82:97]
	s_waitcnt lgkmcnt(9)
	v_mfma_f32_32x32x16_bf16 v[98:113], v[230:233], v[114:117], v[98:113]
	s_waitcnt lgkmcnt(8)
	v_mfma_f32_32x32x16_bf16 v[82:97], v[234:237], v[114:117], v[82:97]
	ds_read_b64_tr_b16 v[210:211], v238 offset:0x200
	ds_read_b64_tr_b16 v[212:213], v238 offset:0xa00
	ds_read_b64_tr_b16 v[214:215], v238 offset:0x1200
	ds_read_b64_tr_b16 v[216:217], v238 offset:0x1a00
	ds_read_b64_tr_b16 v[218:219], v238 offset:0x2200
	ds_read_b64_tr_b16 v[220:221], v238 offset:0x2a00
	ds_read_b64_tr_b16 v[222:223], v238 offset:0x3200
	ds_read_b64_tr_b16 v[224:225], v238 offset:0x3a00
	s_waitcnt lgkmcnt(14)
	v_mfma_f32_32x32x16_bf16 v[50:65], v[142:145], v[194:197], v[50:65]
	s_waitcnt lgkmcnt(12)
	v_mfma_f32_32x32x16_bf16 v[50:65], v[138:141], v[198:201], v[50:65]
	s_waitcnt lgkmcnt(10)
	v_mfma_f32_32x32x16_bf16 v[50:65], v[134:137], v[202:205], v[50:65]
	s_waitcnt lgkmcnt(8)
	v_mfma_f32_32x32x16_bf16 v[50:65], v[130:133], v[206:209], v[50:65]
	ds_read_b64_tr_b16 v[194:195], v238 offset:0x400
	ds_read_b64_tr_b16 v[196:197], v238 offset:0xc00
	ds_read_b64_tr_b16 v[198:199], v238 offset:0x1400
	ds_read_b64_tr_b16 v[200:201], v238 offset:0x1c00
	ds_read_b64_tr_b16 v[202:203], v238 offset:0x2400
	ds_read_b64_tr_b16 v[204:205], v238 offset:0x2c00
	ds_read_b64_tr_b16 v[206:207], v238 offset:0x3400
	ds_read_b64_tr_b16 v[208:209], v238 offset:0x3c00
	s_waitcnt lgkmcnt(14)
	v_mfma_f32_32x32x16_bf16 v[34:49], v[142:145], v[210:213], v[34:49]
	s_waitcnt lgkmcnt(12)
	v_mfma_f32_32x32x16_bf16 v[34:49], v[138:141], v[214:217], v[34:49]
	s_waitcnt lgkmcnt(10)
	v_mfma_f32_32x32x16_bf16 v[34:49], v[134:137], v[218:221], v[34:49]
	s_waitcnt lgkmcnt(8)
	v_mfma_f32_32x32x16_bf16 v[34:49], v[130:133], v[222:225], v[34:49]
	ds_read_b64_tr_b16 v[210:211], v238 offset:0x600
	ds_read_b64_tr_b16 v[212:213], v238 offset:0xe00
	ds_read_b64_tr_b16 v[214:215], v238 offset:0x1600
	ds_read_b64_tr_b16 v[216:217], v238 offset:0x1e00
	ds_read_b64_tr_b16 v[218:219], v238 offset:0x2600
	ds_read_b64_tr_b16 v[220:221], v238 offset:0x2e00
	ds_read_b64_tr_b16 v[222:223], v238 offset:0x3600
	ds_read_b64_tr_b16 v[224:225], v238 offset:0x3e00
	s_waitcnt lgkmcnt(14)
	v_mfma_f32_32x32x16_bf16 v[18:33], v[142:145], v[194:197], v[18:33]
	s_waitcnt lgkmcnt(12)
	v_mfma_f32_32x32x16_bf16 v[18:33], v[138:141], v[198:201], v[18:33]
	s_waitcnt lgkmcnt(10)
	v_mfma_f32_32x32x16_bf16 v[18:33], v[134:137], v[202:205], v[18:33]
	s_waitcnt lgkmcnt(8)
	v_mfma_f32_32x32x16_bf16 v[18:33], v[130:133], v[206:209], v[18:33]
	s_waitcnt lgkmcnt(6)
	v_mfma_f32_32x32x16_bf16 v[2:17], v[142:145], v[210:213], v[2:17]
	s_waitcnt lgkmcnt(4)
	v_mfma_f32_32x32x16_bf16 v[2:17], v[138:141], v[214:217], v[2:17]
	s_waitcnt lgkmcnt(2)
	v_mfma_f32_32x32x16_bf16 v[2:17], v[134:137], v[218:221], v[2:17]
	s_waitcnt lgkmcnt(0)
	v_mfma_f32_32x32x16_bf16 v[2:17], v[130:133], v[222:225], v[2:17]
	s_and_b64 vcc, exec, s[6:7]
	s_cbranch_vccnz .LBB0_601
	s_waitcnt vmcnt(1)

.LBB0_625:
	v_add_f32_e32 v84, v195, v196
	v_fmac_f32_e32 v84, v184, v194
	v_add_f32_e32 v184, v82, v83
	v_fmac_f32_e32 v184, v84, v197
	s_add_i32 s96, s96, 2
	s_and_b64 vcc, exec, s[0:1]
	s_cbranch_vccnz .Lrot_da_exit
	s_mov_b32 s0, s12
	s_mov_b32 s12, s75
	s_mov_b32 s75, s74
	s_mov_b32 s74, s0
	v_add_u32_e32 v238, s74, v193
	s_branch .LBB0_599
.Lrot_da_exit:
	s_barrier
	s_branch .LBB0_629

.LBB0_665:
	v_add_f32_e32 v151, v18, v19
	v_lshlrev_b32_e32 v18, 1, v50
	v_and_b32_e32 v18, 32, v18
	v_and_or_b32 v18, v51, s67, v18
	v_and_b32_e32 v19, 0x100, v52
	v_fmac_f32_e32 v151, 0, v58
	v_or3_b32 v158, v18, v19, v53
	v_add_u32_e32 v187, v57, v56
	v_add_u32_e32 v188, 0, v56
	v_cmp_gt_u32_e64 s[4:5], 32, v50
	v_lshl_add_u32 v157, v54, 2, s18
	v_lshlrev_b32_e32 v156, 4, v55
	v_mov_b64_e32 v[32:33], v[16:17]
	v_mov_b64_e32 v[48:49], v[16:17]
	v_mov_b64_e32 v[64:65], v[16:17]
	s_mov_b32 s93, 1
	v_add_u32_e32 v185, s35, v158
	s_mov_b32 s95, 0x8000
	s_movk_i32 s94, 0x4000
	s_mov_b32 s8, 0
	v_mov_b64_e32 v[30:31], v[14:15]
	v_mov_b64_e32 v[28:29], v[12:13]
	v_mov_b64_e32 v[26:27], v[10:11]
	v_mov_b64_e32 v[24:25], v[8:9]
	v_mov_b64_e32 v[22:23], v[6:7]
	v_mov_b64_e32 v[20:21], v[4:5]
	v_mov_b64_e32 v[18:19], v[2:3]
	v_mov_b64_e32 v[46:47], v[14:15]
	v_mov_b64_e32 v[44:45], v[12:13]
	v_mov_b64_e32 v[42:43], v[10:11]
	v_mov_b64_e32 v[40:41], v[8:9]
	v_mov_b64_e32 v[38:39], v[6:7]
	v_mov_b64_e32 v[36:37], v[4:5]
	v_mov_b64_e32 v[34:35], v[2:3]
	v_mov_b64_e32 v[62:63], v[14:15]
	v_mov_b64_e32 v[60:61], v[12:13]
	v_mov_b64_e32 v[58:59], v[10:11]
	v_mov_b64_e32 v[56:57], v[8:9]
	v_mov_b64_e32 v[54:55], v[6:7]
	v_mov_b64_e32 v[52:53], v[4:5]
	v_mov_b64_e32 v[50:51], v[2:3]
	v_add_u32_e32 v189, v187, v160
	v_add_u32_e32 v190, v187, v162
	v_add_u32_e32 v191, v187, v164
	v_add_u32_e32 v192, v187, v166
.LBB0_666:
	s_barrier
	s_setprio 3
	ds_read_b128 v[66:69], v189 offset:16384
	ds_read_b128 v[70:73], v189 offset:24576
	ds_read_b128 v[194:197], v190 offset:16384
	ds_read_b128 v[198:201], v190 offset:24576
	ds_read_b128 v[202:205], v191 offset:16384
	ds_read_b128 v[206:209], v191 offset:24576
	ds_read_b128 v[210:213], v192 offset:16384
	ds_read_b128 v[214:217], v192 offset:24576
	s_mov_b32 s12, s94
	s_mov_b32 s94, s8
	v_add_u32_e32 v250, s94, v185
	s_waitcnt lgkmcnt(7)
	v_mfma_f32_32x32x16_bf16 v[82:97], v[66:69], v[114:117], 0
	s_waitcnt lgkmcnt(6)
	v_mfma_f32_32x32x16_bf16 v[66:81], v[70:73], v[114:117], 0
	s_waitcnt lgkmcnt(5)
	v_mfma_f32_32x32x16_bf16 v[82:97], v[194:197], v[110:113], v[82:97]
	s_waitcnt lgkmcnt(4)
	v_mfma_f32_32x32x16_bf16 v[66:81], v[198:201], v[110:113], v[66:81]
	v_add_u32_e32 v193, v187, v168
	v_add_u32_e32 v194, v187, v170
	ds_read_b128 v[198:201], v193 offset:24576
	ds_read_b128 v[218:221], v194 offset:16384
	ds_read_b128 v[222:225], v194 offset:24576
	ds_read_b128 v[226:229], v193 offset:16384
	ds_read_b128 v[230:233], v159
	s_waitcnt lgkmcnt(8)
	v_mfma_f32_32x32x16_bf16 v[82:97], v[202:205], v[106:109], v[82:97]
	s_waitcnt lgkmcnt(7)
	v_mfma_f32_32x32x16_bf16 v[66:81], v[206:209], v[106:109], v[66:81]
	s_waitcnt lgkmcnt(6)
	v_mfma_f32_32x32x16_bf16 v[82:97], v[210:213], v[102:105], v[82:97]
	s_waitcnt lgkmcnt(5)
	v_mfma_f32_32x32x16_bf16 v[66:81], v[214:217], v[102:105], v[66:81]
	v_add_u32_e32 v195, v187, v172
	v_add_u32_e32 v196, v187, v174
	ds_read_b128 v[202:205], v195 offset:16384
	ds_read_b128 v[206:209], v195 offset:24576
	ds_read_b128 v[210:213], v196 offset:16384
	ds_read_b128 v[214:217], v196 offset:24576
	ds_read_b128 v[234:237], v159 offset:1024
	ds_read_b128 v[238:241], v159 offset:2048
	s_waitcnt lgkmcnt(7)
	v_mfma_f32_32x32x16_bf16 v[82:97], v[226:229], v[98:101], v[82:97]
	v_mfma_f32_32x32x16_bf16 v[66:81], v[198:201], v[98:101], v[66:81]
	s_waitcnt lgkmcnt(6)
	v_mfma_f32_32x32x16_bf16 v[82:97], v[218:221], v[230:233], v[82:97]
	v_mfma_f32_32x32x16_bf16 v[66:81], v[222:225], v[230:233], v[66:81]
	v_add_u32_e32 v197, v188, v177
	v_add_u32_e32 v198, v188, v179
	ds_read_b128 v[218:221], v197 offset:40960
	ds_read_b128 v[222:225], v197 offset:45056
	ds_read_b128 v[226:229], v198 offset:40960
	ds_read_b128 v[230:233], v198 offset:45056
	ds_read_b128 v[242:245], v159 offset:3072
	ds_read_b128 v[246:249], v159 offset:4096
	s_waitcnt lgkmcnt(7)
	v_mfma_f32_32x32x16_bf16 v[82:97], v[202:205], v[234:237], v[82:97]
	v_mfma_f32_32x32x16_bf16 v[66:81], v[206:209], v[234:237], v[66:81]
	s_waitcnt lgkmcnt(6)
	v_mfma_f32_32x32x16_bf16 v[82:97], v[210:213], v[238:241], v[82:97]
	v_mfma_f32_32x32x16_bf16 v[66:81], v[214:217], v[238:241], v[66:81]
	v_add_u32_e32 v199, v188, v181
	v_add_u32_e32 v200, v188, v183
	ds_read_b128 v[202:205], v199 offset:40960
	ds_read_b128 v[206:209], v199 offset:45056
	ds_read_b128 v[210:213], v200 offset:40960
	ds_read_b128 v[214:217], v200 offset:45056
	ds_read_b128 v[234:237], v159 offset:5120
	ds_read_b128 v[238:241], v159 offset:6144
	s_waitcnt lgkmcnt(7)
	v_mfma_f32_32x32x16_bf16 v[82:97], v[218:221], v[242:245], v[82:97]
	v_mfma_f32_32x32x16_bf16 v[66:81], v[222:225], v[242:245], v[66:81]
	s_waitcnt lgkmcnt(6)
	v_mfma_f32_32x32x16_bf16 v[82:97], v[226:229], v[246:249], v[82:97]
	v_mfma_f32_32x32x16_bf16 v[66:81], v[230:233], v[246:249], v[66:81]
	s_waitcnt lgkmcnt(1)
	v_mfma_f32_32x32x16_bf16 v[82:97], v[202:205], v[234:237], v[82:97]
	v_mfma_f32_32x32x16_bf16 v[66:81], v[206:209], v[234:237], v[66:81]
	s_waitcnt lgkmcnt(0)
	v_mfma_f32_32x32x16_bf16 v[82:97], v[210:213], v[238:241], v[82:97]
	v_mfma_f32_32x32x16_bf16 v[66:81], v[214:217], v[238:241], v[66:81]
	ds_read_b64_tr_b16 v[202:203], v250 offset:0
	ds_read_b64_tr_b16 v[204:205], v250 offset:0x800
	ds_read_b64_tr_b16 v[206:207], v250 offset:0x1000
	ds_read_b64_tr_b16 v[208:209], v250 offset:0x1800
	ds_read_b64_tr_b16 v[210:211], v250 offset:0x2000
	ds_read_b64_tr_b16 v[212:213], v250 offset:0x2800
	ds_read_b64_tr_b16 v[214:215], v250 offset:0x3000
	ds_read_b64_tr_b16 v[216:217], v250 offset:0x3800
	ds_read_b64_tr_b16 v[218:219], v250 offset:0x200
	ds_read_b64_tr_b16 v[220:221], v250 offset:0xa00
	ds_read_b64_tr_b16 v[222:223], v250 offset:0x1200
	ds_read_b64_tr_b16 v[224:225], v250 offset:0x1a00
	ds_read_b64_tr_b16 v[226:227], v250 offset:0x2200
	ds_read_b64_tr_b16 v[228:229], v250 offset:0x2a00
	ds_read_b64_tr_b16 v[230:231], v250 offset:0x3200
	ds_read_b64_tr_b16 v[232:233], v250 offset:0x3a00
	s_nop 0
	s_waitcnt lgkmcnt(14)
	v_mfma_f32_32x32x16_bf16 v[50:65], v[130:133], v[202:205], v[50:65]
	s_waitcnt lgkmcnt(12)
	v_mfma_f32_32x32x16_bf16 v[50:65], v[126:129], v[206:209], v[50:65]
	s_waitcnt lgkmcnt(10)
	v_mfma_f32_32x32x16_bf16 v[50:65], v[122:125], v[210:213], v[50:65]
	s_waitcnt lgkmcnt(8)
	v_mfma_f32_32x32x16_bf16 v[50:65], v[118:121], v[214:217], v[50:65]
	ds_read_b64_tr_b16 v[202:203], v250 offset:0x400
	ds_read_b64_tr_b16 v[204:205], v250 offset:0xc00
	ds_read_b64_tr_b16 v[206:207], v250 offset:0x1400
	ds_read_b64_tr_b16 v[208:209], v250 offset:0x1c00
	ds_read_b64_tr_b16 v[210:211], v250 offset:0x2400
	ds_read_b64_tr_b16 v[212:213], v250 offset:0x2c00
	ds_read_b64_tr_b16 v[214:215], v250 offset:0x3400
	ds_read_b64_tr_b16 v[216:217], v250 offset:0x3c00
	s_waitcnt lgkmcnt(14)
	v_mfma_f32_32x32x16_bf16 v[34:49], v[130:133], v[218:221], v[34:49]
	s_waitcnt lgkmcnt(12)
	v_mfma_f32_32x32x16_bf16 v[34:49], v[126:129], v[222:225], v[34:49]
	s_waitcnt lgkmcnt(10)
	v_mfma_f32_32x32x16_bf16 v[34:49], v[122:125], v[226:229], v[34:49]
	s_waitcnt lgkmcnt(8)
	v_mfma_f32_32x32x16_bf16 v[34:49], v[118:121], v[230:233], v[34:49]
	ds_read_b64_tr_b16 v[218:219], v250 offset:0x600
	ds_read_b64_tr_b16 v[220:221], v250 offset:0xe00
	ds_read_b64_tr_b16 v[222:223], v250 offset:0x1600
	ds_read_b64_tr_b16 v[224:225], v250 offset:0x1e00
	ds_read_b64_tr_b16 v[226:227], v250 offset:0x2600
	ds_read_b64_tr_b16 v[228:229], v250 offset:0x2e00
	ds_read_b64_tr_b16 v[230:231], v250 offset:0x3600
	ds_read_b64_tr_b16 v[232:233], v250 offset:0x3e00
	s_waitcnt lgkmcnt(14)
	v_mfma_f32_32x32x16_bf16 v[18:33], v[130:133], v[202:205], v[18:33]
	s_waitcnt lgkmcnt(12)
	v_mfma_f32_32x32x16_bf16 v[18:33], v[126:129], v[206:209], v[18:33]
	s_waitcnt lgkmcnt(10)
	v_mfma_f32_32x32x16_bf16 v[18:33], v[122:125], v[210:213], v[18:33]
	s_waitcnt lgkmcnt(8)
	v_mfma_f32_32x32x16_bf16 v[18:33], v[118:121], v[214:217], v[18:33]
	s_waitcnt lgkmcnt(6)
	v_mfma_f32_32x32x16_bf16 v[2:17], v[130:133], v[218:221], v[2:17]
	s_waitcnt lgkmcnt(4)
	v_mfma_f32_32x32x16_bf16 v[2:17], v[126:129], v[222:225], v[2:17]
	s_waitcnt lgkmcnt(2)
	v_mfma_f32_32x32x16_bf16 v[2:17], v[122:125], v[226:229], v[2:17]
	s_waitcnt lgkmcnt(0)
	v_mfma_f32_32x32x16_bf16 v[2:17], v[118:121], v[230:233], v[2:17]
	s_and_b64 vcc, exec, s[6:7]
	s_cbranch_vccnz .LBB0_668
	s_waitcnt vmcnt(0)

.LBB0_690:
	v_add_f32_e32 v68, v202, v203
	v_fmac_f32_e32 v68, v151, v201
	v_add_f32_e32 v151, v66, v67
	v_fmac_f32_e32 v151, v68, v204
	s_add_i32 s93, s93, 2
	s_and_b64 vcc, exec, s[56:57]
	s_cbranch_vccnz .Lrot_mla_exit
	s_mov_b32 s8, s95
	s_mov_b32 s95, s12
	v_add_u32_e32 v189, v187, v160
	v_add_u32_e32 v190, v187, v162
	v_add_u32_e32 v191, v187, v164
	v_add_u32_e32 v192, v187, v166
	s_branch .LBB0_666
.Lrot_mla_exit:
	s_barrier
.LBB0_692:
	ds_read_b128 v[66:69], v189 offset:16384
	ds_read_b128 v[70:73], v189 offset:24576
	ds_read_b128 v[142:145], v190 offset:16384
	ds_read_b128 v[152:155], v190 offset:24576
	ds_read_b128 v[160:163], v191 offset:16384
	ds_read_b128 v[164:167], v191 offset:24576
	ds_read_b128 v[168:171], v192 offset:16384
	ds_read_b128 v[172:175], v192 offset:24576
	v_add_u32_e32 v134, s60, v158
	s_waitcnt lgkmcnt(0)
	v_mfma_f32_32x32x16_bf16 v[82:97], v[66:69], v[114:117], 0
	v_mfma_f32_32x32x16_bf16 v[66:81], v[70:73], v[114:117], 0
	v_mfma_f32_32x32x16_bf16 v[82:97], v[142:145], v[110:113], v[82:97]
	v_mfma_f32_32x32x16_bf16 v[66:81], v[152:155], v[110:113], v[66:81]
	ds_read_b128 v[110:113], v193 offset:24576
	ds_read_b128 v[114:117], v194 offset:16384
	ds_read_b128 v[142:145], v194 offset:24576
	ds_read_b128 v[152:155], v193 offset:16384
	ds_read_b128 v[178:181], v159
	v_mfma_f32_32x32x16_bf16 v[82:97], v[160:163], v[106:109], v[82:97]
	v_mfma_f32_32x32x16_bf16 v[66:81], v[164:167], v[106:109], v[66:81]
	v_mfma_f32_32x32x16_bf16 v[82:97], v[168:171], v[102:105], v[82:97]
	v_mfma_f32_32x32x16_bf16 v[66:81], v[172:175], v[102:105], v[66:81]
	ds_read_b128 v[102:105], v195 offset:16384
	ds_read_b128 v[106:109], v195 offset:24576
	ds_read_b128 v[160:163], v196 offset:16384
	ds_read_b128 v[164:167], v196 offset:24576
	ds_read_b128 v[168:171], v159 offset:1024
	ds_read_b128 v[172:175], v159 offset:2048
	s_waitcnt lgkmcnt(0)
	v_mfma_f32_32x32x16_bf16 v[82:97], v[152:155], v[98:101], v[82:97]
	v_mfma_f32_32x32x16_bf16 v[66:81], v[110:113], v[98:101], v[66:81]
	v_mfma_f32_32x32x16_bf16 v[82:97], v[114:117], v[178:181], v[82:97]
	v_mfma_f32_32x32x16_bf16 v[66:81], v[142:145], v[178:181], v[66:81]
	ds_read_b128 v[98:101], v197 offset:40960
	ds_read_b128 v[110:113], v197 offset:45056
	ds_read_b128 v[114:117], v198 offset:40960
	ds_read_b128 v[142:145], v198 offset:45056
	ds_read_b128 v[152:155], v159 offset:3072
	ds_read_b128 v[178:181], v159 offset:4096
	v_mfma_f32_32x32x16_bf16 v[82:97], v[102:105], v[168:171], v[82:97]
	v_mfma_f32_32x32x16_bf16 v[66:81], v[106:109], v[168:171], v[66:81]
	v_mfma_f32_32x32x16_bf16 v[82:97], v[160:163], v[172:175], v[82:97]
	v_mfma_f32_32x32x16_bf16 v[66:81], v[164:167], v[172:175], v[66:81]
	ds_read_b128 v[102:105], v199 offset:40960
	ds_read_b128 v[106:109], v199 offset:45056
	ds_read_b128 v[160:163], v200 offset:40960
	ds_read_b128 v[164:167], v200 offset:45056
	ds_read_b128 v[168:171], v159 offset:5120
	ds_read_b128 v[172:175], v159 offset:6144
	s_waitcnt lgkmcnt(0)
	v_mfma_f32_32x32x16_bf16 v[82:97], v[98:101], v[152:155], v[82:97]
	v_mfma_f32_32x32x16_bf16 v[66:81], v[110:113], v[152:155], v[66:81]
	v_mfma_f32_32x32x16_bf16 v[82:97], v[114:117], v[178:181], v[82:97]
	v_mfma_f32_32x32x16_bf16 v[66:81], v[142:145], v[178:181], v[66:81]
	v_mfma_f32_32x32x16_bf16 v[82:97], v[102:105], v[168:171], v[82:97]
	v_mfma_f32_32x32x16_bf16 v[66:81], v[106:109], v[168:171], v[66:81]
	v_mfma_f32_32x32x16_bf16 v[82:97], v[160:163], v[172:175], v[82:97]
	v_mfma_f32_32x32x16_bf16 v[66:81], v[164:167], v[172:175], v[66:81]
	ds_read_b64_tr_b16 v[98:99], v134 offset:0
	ds_read_b64_tr_b16 v[100:101], v134 offset:0x800
	ds_read_b64_tr_b16 v[102:103], v134 offset:0x1000
	ds_read_b64_tr_b16 v[104:105], v134 offset:0x1800
	ds_read_b64_tr_b16 v[106:107], v134 offset:0x2000
	ds_read_b64_tr_b16 v[108:109], v134 offset:0x2800
	ds_read_b64_tr_b16 v[110:111], v134 offset:0x3000
	ds_read_b64_tr_b16 v[112:113], v134 offset:0x3800
	ds_read_b64_tr_b16 v[114:115], v134 offset:0x200
	ds_read_b64_tr_b16 v[116:117], v134 offset:0xa00
	ds_read_b64_tr_b16 v[142:143], v134 offset:0x1200
	ds_read_b64_tr_b16 v[144:145], v134 offset:0x1a00
	ds_read_b64_tr_b16 v[152:153], v134 offset:0x2200
	ds_read_b64_tr_b16 v[154:155], v134 offset:0x2a00
	ds_read_b64_tr_b16 v[160:161], v134 offset:0x3200
	ds_read_b64_tr_b16 v[162:163], v134 offset:0x3a00
	s_waitcnt lgkmcnt(8)
	s_nop 0
	v_mfma_f32_32x32x16_bf16 v[50:65], v[130:133], v[98:101], v[50:65]
	v_mfma_f32_32x32x16_bf16 v[50:65], v[126:129], v[102:105], v[50:65]
	v_mfma_f32_32x32x16_bf16 v[50:65], v[122:125], v[106:109], v[50:65]
	v_mfma_f32_32x32x16_bf16 v[50:65], v[118:121], v[110:113], v[50:65]
	ds_read_b64_tr_b16 v[98:99], v134 offset:0x400
	ds_read_b64_tr_b16 v[100:101], v134 offset:0xc00
	ds_read_b64_tr_b16 v[102:103], v134 offset:0x1400
	ds_read_b64_tr_b16 v[104:105], v134 offset:0x1c00
	ds_read_b64_tr_b16 v[106:107], v134 offset:0x2400
	ds_read_b64_tr_b16 v[108:109], v134 offset:0x2c00
	ds_read_b64_tr_b16 v[110:111], v134 offset:0x3400
	ds_read_b64_tr_b16 v[112:113], v134 offset:0x3c00
	s_waitcnt lgkmcnt(8)
	v_mfma_f32_32x32x16_bf16 v[34:49], v[130:133], v[114:117], v[34:49]
	v_mfma_f32_32x32x16_bf16 v[34:49], v[126:129], v[142:145], v[34:49]
	v_mfma_f32_32x32x16_bf16 v[34:49], v[122:125], v[152:155], v[34:49]
	v_mfma_f32_32x32x16_bf16 v[34:49], v[118:121], v[160:163], v[34:49]
	ds_read_b64_tr_b16 v[114:115], v134 offset:0x600
	ds_read_b64_tr_b16 v[116:117], v134 offset:0xe00
	ds_read_b64_tr_b16 v[142:143], v134 offset:0x1600
	ds_read_b64_tr_b16 v[144:145], v134 offset:0x1e00
	ds_read_b64_tr_b16 v[152:153], v134 offset:0x2600
	ds_read_b64_tr_b16 v[154:155], v134 offset:0x2e00
	ds_read_b64_tr_b16 v[160:161], v134 offset:0x3600
	ds_read_b64_tr_b16 v[162:163], v134 offset:0x3e00
	s_waitcnt lgkmcnt(8)
	v_mfma_f32_32x32x16_bf16 v[18:33], v[130:133], v[98:101], v[18:33]
	v_mfma_f32_32x32x16_bf16 v[18:33], v[126:129], v[102:105], v[18:33]
	v_mfma_f32_32x32x16_bf16 v[18:33], v[122:125], v[106:109], v[18:33]
	v_mfma_f32_32x32x16_bf16 v[18:33], v[118:121], v[110:113], v[18:33]
	s_waitcnt lgkmcnt(0)
	v_mfma_f32_32x32x16_bf16 v[2:17], v[130:133], v[114:117], v[2:17]
	v_mfma_f32_32x32x16_bf16 v[2:17], v[126:129], v[142:145], v[2:17]
	v_mfma_f32_32x32x16_bf16 v[2:17], v[122:125], v[152:155], v[2:17]
	v_mfma_f32_32x32x16_bf16 v[2:17], v[118:121], v[160:163], v[2:17]
	s_and_b64 vcc, exec, s[44:45]
	s_cbranch_vccz .LBB0_694
	s_waitcnt vmcnt(0)
